# attention v2: -mhat in MFMA C operand, in-place packed P, scalar row sums, 4-slot ring, waves 4-7 staggered half a step
# baseline (speedup 1.0000x reference)
.LBB0_409:
	s_and_b64 vcc, exec, s[0:1]
	s_cbranch_vccz .LBB0_492
	v_readlane_b32 s0, v255, 12
	s_cmpk_gt_i32 s0, 0x7ff
	s_cbranch_scc1 .LBB0_492
	s_mov_b32 s24, m0
	v_readfirstlane_b32 s4, v198
	v_readlane_b32 s38, v255, 12
	s_lshr_b32 s27, s4, 6
	s_lshl_b32 s16, s27, 10
	s_lshr_b32 s2, s27, 2
	v_and_b32_e32 v228, 31, v246
	v_lshrrev_b32_e32 v229, 5, v246
	v_lshlrev_b32_e32 v200, 10, v246
	s_lshl_b32 s4, s27, 4
	v_add_u32_e32 v200, s4, v200
	v_lshrrev_b32_e32 v230, 2, v246
	s_and_b32 s4, s27, 3
	s_lshl_b32 s4, s4, 4
	v_add_u32_e32 v230, s4, v230
	v_lshlrev_b32_e32 v230, 10, v230
	v_and_b32_e32 v231, 3, v246
	v_lshlrev_b32_e32 v231, 4, v231
	s_lshr_b32 s4, s27, 2
	s_lshl_b32 s4, s4, 6
	v_add3_u32 v201, v230, v231, s4
	v_add_u32_e32 v202, 0x80, v201
	s_lshl_b32 s4, s27, 5
	v_add_u32_e32 v230, s4, v228
	v_lshlrev_b32_e32 v225, 10, v230
	v_lshl_add_u32 v225, v229, 4, v225
	v_lshlrev_b32_e32 v231, 2, v229
	v_sub_u32_e32 v218, v230, v231
	v_lshlrev_b32_e32 v203, 10, v229
	v_lshl_add_u32 v203, v228, 4, v203
	v_bfe_u32 v230, v246, 4, 1
	v_lshlrev_b32_e32 v230, 5, v230
	v_and_b32_e32 v231, 3, v246
	v_lshl_add_u32 v230, v231, 3, v230
	v_bfe_u32 v231, v246, 2, 2
	v_lshl_add_u32 v231, v229, 2, v231
	v_lshl_add_u32 v230, v231, 6, v230
	v_add_u32_e32 v204, 0x8000, v230
	s_lshl_b32 s4, s27, 8
	s_add_i32 s4, s4, 0x18000
	v_lshl_add_u32 v220, v228, 2, s4
	v_lshl_add_u32 v221, v229, 4, s4
	s_lshl_b32 s4, s27, 11
	s_add_i32 s4, s4, 0x18800
	v_lshlrev_b32_e32 v230, 8, v229
	v_lshl_add_u32 v230, v228, 1, v230
	v_add_u32_e32 v222, s4, v230
	v_lshrrev_b32_e32 v230, 2, v246
	v_and_b32_e32 v231, 3, v246
	v_lshlrev_b32_e32 v223, 6, v230
	v_lshl_add_u32 v223, v231, 4, v223
	v_add_u32_e32 v223, s4, v223
	s_lshl_b32 s4, s27, 5
	v_add_u32_e32 v230, s4, v230
	v_lshlrev_b32_e32 v224, 11, v230
	v_lshl_add_u32 v224, v231, 4, v224
	v_mov_b32_e32 v219, 0xff800000
	s_mov_b32 s26, 0
.Lat2_unit_1:
	s_and_b32 s4, s38, 3
	s_lshl_b32 s4, s4, 1
	s_lshr_b32 s5, s26, 1
	s_add_i32 s4, s4, s5
	s_sub_i32 s5, 15, s4
	s_bitcmp1_b32 s26, 0
	s_cselect_b32 s4, s5, s4
	s_lshl_b32 s39, s4, 2
	s_add_i32 s39, s39, 4
	s_sub_i32 s18, s39, 4
	s_lshr_b32 s5, s38, 5
	s_lshl_b32 s5, s5, 12
	s_lshl_b32 s6, s4, 8
	s_add_i32 s6, s6, s5
	s_bfe_u32 s7, s38, 0x30002
	s_lshl_b32 s14, s6, 10
	s_lshl_b32 s15, s7, 7
	s_add_i32 s14, s14, s15
	s_add_u32 s72, s54, s14
	s_addc_u32 s73, s55, 0
	s_lshl_b32 s14, s5, 10
	s_add_i32 s15, s14, s15
	s_add_i32 s15, s15, 0x2000000
	s_add_u32 s74, s54, s15
	s_addc_u32 s75, s55, 0
	s_lshr_b32 s15, s7, 1
	s_lshl_b32 s15, s15, 8
	s_add_i32 s14, s14, s15
	s_add_u32 s76, s64, s14
	s_addc_u32 s77, s65, 0
	s_lshl_b32 s14, s6, 11
	s_lshl_b32 s15, s7, 8
	s_add_i32 s14, s14, s15
	s_add_u32 s78, s50, s14
	s_addc_u32 s79, s51, 0
	global_load_dwordx4 v[148:151], v225, s[72:73] offset:0
	global_load_dwordx4 v[152:155], v225, s[72:73] offset:32
	global_load_dwordx4 v[156:159], v225, s[72:73] offset:64
	global_load_dwordx4 v[160:163], v225, s[72:73] offset:96
	s_mov_b64 s[80:81], s[74:75]
	s_mov_b64 s[82:83], s[76:77]
	s_mov_b32 s59, 0
	s_mov_b32 s60, 0x2000
	s_mov_b32 s61, 0x4000
	s_mov_b32 s25, 0x6000
	s_add_i32 s4, s59, s16
	s_mov_b32 m0, s4
	s_lshl_b32 s5, s59, 1
	global_load_lds_dwordx4 v200, s[80:81]
	s_add_i32 s5, s5, s16
	s_add_i32 s5, s5, 0x8000
	s_mov_b32 m0, s5
	s_add_i32 s5, s5, 0x2000
	global_load_lds_dwordx4 v201, s[82:83]
	s_mov_b32 m0, s5
	s_nop 0
	global_load_lds_dwordx4 v202, s[82:83]
	s_add_u32 s80, s80, 0x10000
	s_addc_u32 s81, s81, 0
	s_add_u32 s82, s82, 0x10000
	s_addc_u32 s83, s83, 0
	s_add_i32 s4, s60, s16
	s_mov_b32 m0, s4
	s_lshl_b32 s5, s60, 1
	global_load_lds_dwordx4 v200, s[80:81]
	s_add_i32 s5, s5, s16
	s_add_i32 s5, s5, 0x8000
	s_mov_b32 m0, s5
	s_add_i32 s5, s5, 0x2000
	global_load_lds_dwordx4 v201, s[82:83]
	s_mov_b32 m0, s5
	s_nop 0
	global_load_lds_dwordx4 v202, s[82:83]
	s_add_u32 s80, s80, 0x10000
	s_addc_u32 s81, s81, 0
	s_add_u32 s82, s82, 0x10000
	s_addc_u32 s83, s83, 0
	v_mov_b32_e32 v0, 0
	v_mov_b32_e32 v1, 0
	v_mov_b32_e32 v2, 0
	v_mov_b32_e32 v3, 0
	v_mov_b32_e32 v4, 0
	v_mov_b32_e32 v5, 0
	v_mov_b32_e32 v6, 0
	v_mov_b32_e32 v7, 0
	v_mov_b32_e32 v8, 0
	v_mov_b32_e32 v9, 0
	v_mov_b32_e32 v10, 0
	v_mov_b32_e32 v11, 0
	v_mov_b32_e32 v12, 0
	v_mov_b32_e32 v13, 0
	v_mov_b32_e32 v14, 0
	v_mov_b32_e32 v15, 0
	v_mov_b32_e32 v16, 0
	v_mov_b32_e32 v17, 0
	v_mov_b32_e32 v18, 0
	v_mov_b32_e32 v19, 0
	v_mov_b32_e32 v20, 0
	v_mov_b32_e32 v21, 0
	v_mov_b32_e32 v22, 0
	v_mov_b32_e32 v23, 0
	v_mov_b32_e32 v24, 0
	v_mov_b32_e32 v25, 0
	v_mov_b32_e32 v26, 0
	v_mov_b32_e32 v27, 0
	v_mov_b32_e32 v28, 0
	v_mov_b32_e32 v29, 0
	v_mov_b32_e32 v30, 0
	v_mov_b32_e32 v31, 0
	v_mov_b32_e32 v32, 0
	v_mov_b32_e32 v33, 0
	v_mov_b32_e32 v34, 0
	v_mov_b32_e32 v35, 0
	v_mov_b32_e32 v36, 0
	v_mov_b32_e32 v37, 0
	v_mov_b32_e32 v38, 0
	v_mov_b32_e32 v39, 0
	v_mov_b32_e32 v40, 0
	v_mov_b32_e32 v41, 0
	v_mov_b32_e32 v42, 0
	v_mov_b32_e32 v43, 0
	v_mov_b32_e32 v44, 0
	v_mov_b32_e32 v45, 0
	v_mov_b32_e32 v46, 0
	v_mov_b32_e32 v47, 0
	v_mov_b32_e32 v48, 0
	v_mov_b32_e32 v49, 0
	v_mov_b32_e32 v50, 0
	v_mov_b32_e32 v51, 0
	v_mov_b32_e32 v52, 0
	v_mov_b32_e32 v53, 0
	v_mov_b32_e32 v54, 0
	v_mov_b32_e32 v55, 0
	v_mov_b32_e32 v56, 0
	v_mov_b32_e32 v57, 0
	v_mov_b32_e32 v58, 0
	v_mov_b32_e32 v59, 0
	v_mov_b32_e32 v60, 0
	v_mov_b32_e32 v61, 0
	v_mov_b32_e32 v62, 0
	v_mov_b32_e32 v63, 0
	v_mov_b32_e32 v100, 0
	v_mov_b32_e32 v101, 0
	v_mov_b32_e32 v102, 0
	v_mov_b32_e32 v103, 0
	v_mov_b32_e32 v104, 0
	v_mov_b32_e32 v105, 0
	v_mov_b32_e32 v106, 0
	v_mov_b32_e32 v107, 0
	v_mov_b32_e32 v108, 0
	v_mov_b32_e32 v109, 0
	v_mov_b32_e32 v110, 0
	v_mov_b32_e32 v111, 0
	v_mov_b32_e32 v112, 0
	v_mov_b32_e32 v113, 0
	v_mov_b32_e32 v114, 0
	v_mov_b32_e32 v115, 0
	v_mov_b32_e32 v210, 0
	v_mov_b32_e32 v232, 0
	v_mov_b32_e32 v233, 0
	v_mov_b32_e32 v234, 0
	v_mov_b32_e32 v235, 0
	s_mov_b32 s62, 0xf149f2ca
	s_mov_b32 s47, 0xf149f2ca
	s_mov_b32 s45, 0
	s_waitcnt vmcnt(3)
	s_barrier
.Lat2_main_2:
	s_cmp_lt_u32 s45, s18
	s_cbranch_scc0 .Lat2_band_3
	v_add_u32_e32 v205, s59, v203
	ds_read_b128 v[116:119], v205 offset:0
	ds_read_b128 v[120:123], v205 offset:512
	ds_read_b128 v[124:127], v205 offset:2048
	ds_read_b128 v[128:131], v205 offset:2560
	ds_read_b128 v[132:135], v205 offset:4096
	ds_read_b128 v[136:139], v205 offset:4608
	ds_read_b128 v[140:143], v205 offset:6144
	ds_read_b128 v[144:147], v205 offset:6656
	s_add_i32 s6, s45, 2
	s_cmp_lt_u32 s6, s39
	s_cbranch_scc0 .Lat2_nodma_6
	s_add_i32 s4, s61, s16
	s_mov_b32 m0, s4
	s_lshl_b32 s5, s61, 1
	global_load_lds_dwordx4 v200, s[80:81]
	s_add_i32 s5, s5, s16
	s_add_i32 s5, s5, 0x8000
	s_mov_b32 m0, s5
	s_add_i32 s5, s5, 0x2000
	global_load_lds_dwordx4 v201, s[82:83]
	s_mov_b32 m0, s5
	s_nop 0
	global_load_lds_dwordx4 v202, s[82:83]
	s_add_u32 s80, s80, 0x10000
	s_addc_u32 s81, s81, 0
	s_add_u32 s82, s82, 0x10000
	s_addc_u32 s83, s83, 0
.Lat2_nodma_6:
	s_lshl_b32 s7, s59, 1
	v_add_u32_e32 v206, s7, v204
	s_waitcnt lgkmcnt(6)
	v_mfma_f32_32x32x16_bf16 v[64:79], v[116:119], v[148:151], v[100:115]
	v_mfma_f32_32x32x16_bf16 v[80:95], v[120:123], v[148:151], v[100:115]
	s_waitcnt lgkmcnt(4)
	v_mfma_f32_32x32x16_bf16 v[64:79], v[124:127], v[152:155], v[64:79]
	v_mfma_f32_32x32x16_bf16 v[80:95], v[128:131], v[152:155], v[80:95]
	s_waitcnt lgkmcnt(2)
	v_mfma_f32_32x32x16_bf16 v[64:79], v[132:135], v[156:159], v[64:79]
	v_mfma_f32_32x32x16_bf16 v[80:95], v[136:139], v[156:159], v[80:95]
	s_waitcnt lgkmcnt(0)
	v_mfma_f32_32x32x16_bf16 v[64:79], v[140:143], v[160:163], v[64:79]
	v_mfma_f32_32x32x16_bf16 v[80:95], v[144:147], v[160:163], v[80:95]
	ds_read_b64_tr_b16 v[164:165], v206 offset:0
	ds_read_b64_tr_b16 v[166:167], v206 offset:512
	ds_read_b64_tr_b16 v[168:169], v206 offset:4096
	ds_read_b64_tr_b16 v[170:171], v206 offset:4608
	ds_read_b64_tr_b16 v[172:173], v206 offset:8192
	ds_read_b64_tr_b16 v[174:175], v206 offset:8704
	ds_read_b64_tr_b16 v[176:177], v206 offset:12288
	ds_read_b64_tr_b16 v[178:179], v206 offset:12800
	ds_read_b64_tr_b16 v[180:181], v206 offset:1024
	ds_read_b64_tr_b16 v[182:183], v206 offset:1536
	ds_read_b64_tr_b16 v[184:185], v206 offset:5120
	ds_read_b64_tr_b16 v[186:187], v206 offset:5632
	ds_read_b64_tr_b16 v[188:189], v206 offset:9216
	ds_read_b64_tr_b16 v[190:191], v206 offset:9728
	ds_read_b64_tr_b16 v[192:193], v206 offset:13312
	ds_read_b64_tr_b16 v[194:195], v206 offset:13824
	s_nop 0
	s_nop 0
	v_max3_f32 v215, v64, v65, v80
	v_max3_f32 v216, v66, v67, v81
	v_max3_f32 v215, v215, v82, v83
	v_max3_f32 v216, v216, v68, v69
	v_max3_f32 v215, v215, v70, v71
	v_max3_f32 v216, v216, v84, v85
	v_max3_f32 v215, v215, v86, v87
	v_max3_f32 v216, v216, v72, v73
	v_max3_f32 v215, v215, v74, v75
	v_max3_f32 v216, v216, v88, v89
	v_max3_f32 v215, v215, v90, v91
	v_max3_f32 v216, v216, v76, v77
	v_max3_f32 v215, v215, v78, v79
	v_max3_f32 v216, v216, v92, v93
	v_max3_f32 v215, v215, v94, v95
	v_max_f32_e32 v214, v215, v216
	v_mov_b32_e32 v215, v214
	s_nop 1
	v_permlane32_swap_b32_e32 v214, v215
	s_nop 0
	v_max_f32_e32 v214, v214, v215
	v_cmp_lt_f32_e32 vcc, s62, v214
	s_cmp_lg_u64 vcc, 0
	s_cbranch_scc1 .Lat2_resc_7
.Lat2_back_8:
	s_cmp_eq_u32 s2, 1
	s_cbranch_scc0 .Lat2_skip_9
	s_add_i32 s6, s45, 2
	s_cmp_lt_u32 s6, s39
	s_cbranch_scc1 .Lat2_w3_10
	s_waitcnt vmcnt(0)
	s_branch .Lat2_wd_11

.Lat2_skip_9:
	v_exp_f32_e32 v64, v64
	v_exp_f32_e32 v65, v65
	v_exp_f32_e32 v66, v66
	v_exp_f32_e32 v67, v67
	v_exp_f32_e32 v68, v68
	v_exp_f32_e32 v69, v69
	v_exp_f32_e32 v70, v70
	v_exp_f32_e32 v71, v71
	s_nop 0
	v_add_f32_e32 v232, v232, v64
	v_add_f32_e32 v233, v233, v65
	v_add_f32_e32 v234, v234, v66
	v_add_f32_e32 v235, v235, v67
	v_add_f32_e32 v232, v232, v68
	v_add_f32_e32 v233, v233, v69
	v_add_f32_e32 v234, v234, v70
	v_add_f32_e32 v235, v235, v71
	v_cvt_pk_bf16_f32 v64, v64, v65
	v_cvt_pk_bf16_f32 v65, v66, v67
	v_cvt_pk_bf16_f32 v66, v68, v69
	v_cvt_pk_bf16_f32 v67, v70, v71
	s_waitcnt lgkmcnt(0)
	s_nop 0
	v_mfma_f32_32x32x16_bf16 v[0:15], v[64:67], v[164:167], v[0:15]
	v_exp_f32_e32 v72, v72
	v_exp_f32_e32 v73, v73
	v_mfma_f32_32x32x16_bf16 v[16:31], v[64:67], v[168:171], v[16:31]
	ds_read_b64_tr_b16 v[164:165], v206 offset:2048
	ds_read_b64_tr_b16 v[166:167], v206 offset:2560
	v_exp_f32_e32 v74, v74
	v_exp_f32_e32 v75, v75
	v_add_f32_e32 v232, v232, v72
	v_add_f32_e32 v233, v233, v73
	v_mfma_f32_32x32x16_bf16 v[32:47], v[64:67], v[172:175], v[32:47]
	ds_read_b64_tr_b16 v[168:169], v206 offset:6144
	ds_read_b64_tr_b16 v[170:171], v206 offset:6656
	v_exp_f32_e32 v76, v76
	v_exp_f32_e32 v77, v77
	v_add_f32_e32 v234, v234, v74
	v_add_f32_e32 v235, v235, v75
	v_mfma_f32_32x32x16_bf16 v[48:63], v[64:67], v[176:179], v[48:63]
	ds_read_b64_tr_b16 v[172:173], v206 offset:10240
	ds_read_b64_tr_b16 v[174:175], v206 offset:10752
	v_exp_f32_e32 v78, v78
	v_exp_f32_e32 v79, v79
	v_add_f32_e32 v232, v232, v76
	v_add_f32_e32 v233, v233, v77
	s_nop 0
	v_add_f32_e32 v234, v234, v78
	v_add_f32_e32 v235, v235, v79
	v_cvt_pk_bf16_f32 v72, v72, v73
	v_cvt_pk_bf16_f32 v73, v74, v75
	v_cvt_pk_bf16_f32 v74, v76, v77
	v_cvt_pk_bf16_f32 v75, v78, v79
	s_nop 1
	v_mfma_f32_32x32x16_bf16 v[0:15], v[72:75], v[180:183], v[0:15]
	ds_read_b64_tr_b16 v[176:177], v206 offset:14336
	ds_read_b64_tr_b16 v[178:179], v206 offset:14848
	v_exp_f32_e32 v80, v80
	v_exp_f32_e32 v81, v81
	v_mfma_f32_32x32x16_bf16 v[16:31], v[72:75], v[184:187], v[16:31]
	ds_read_b64_tr_b16 v[180:181], v206 offset:3072
	ds_read_b64_tr_b16 v[182:183], v206 offset:3584
	v_exp_f32_e32 v82, v82
	v_exp_f32_e32 v83, v83
	v_add_f32_e32 v232, v232, v80
	v_add_f32_e32 v233, v233, v81
	v_mfma_f32_32x32x16_bf16 v[32:47], v[72:75], v[188:191], v[32:47]
	ds_read_b64_tr_b16 v[184:185], v206 offset:7168
	ds_read_b64_tr_b16 v[186:187], v206 offset:7680
	v_exp_f32_e32 v84, v84
	v_exp_f32_e32 v85, v85
	v_add_f32_e32 v234, v234, v82
	v_add_f32_e32 v235, v235, v83
	v_mfma_f32_32x32x16_bf16 v[48:63], v[72:75], v[192:195], v[48:63]
	ds_read_b64_tr_b16 v[188:189], v206 offset:11264
	ds_read_b64_tr_b16 v[190:191], v206 offset:11776
	v_exp_f32_e32 v86, v86
	v_exp_f32_e32 v87, v87
	v_add_f32_e32 v232, v232, v84
	v_add_f32_e32 v233, v233, v85
	s_nop 0
	v_add_f32_e32 v234, v234, v86
	v_add_f32_e32 v235, v235, v87
	v_cvt_pk_bf16_f32 v80, v80, v81
	v_cvt_pk_bf16_f32 v81, v82, v83
	v_cvt_pk_bf16_f32 v82, v84, v85
	v_cvt_pk_bf16_f32 v83, v86, v87
	s_nop 1
	s_waitcnt lgkmcnt(12)
	v_mfma_f32_32x32x16_bf16 v[0:15], v[80:83], v[164:167], v[0:15]
	ds_read_b64_tr_b16 v[192:193], v206 offset:15360
	ds_read_b64_tr_b16 v[194:195], v206 offset:15872
	v_exp_f32_e32 v88, v88
	v_exp_f32_e32 v89, v89
	s_waitcnt lgkmcnt(12)
	v_mfma_f32_32x32x16_bf16 v[16:31], v[80:83], v[168:171], v[16:31]
	v_exp_f32_e32 v90, v90
	v_exp_f32_e32 v91, v91
	v_add_f32_e32 v232, v232, v88
	v_add_f32_e32 v233, v233, v89
	s_waitcnt lgkmcnt(10)
	v_mfma_f32_32x32x16_bf16 v[32:47], v[80:83], v[172:175], v[32:47]
	v_exp_f32_e32 v92, v92
	v_exp_f32_e32 v93, v93
	v_add_f32_e32 v234, v234, v90
	v_add_f32_e32 v235, v235, v91
	s_waitcnt lgkmcnt(8)
	v_mfma_f32_32x32x16_bf16 v[48:63], v[80:83], v[176:179], v[48:63]
	v_exp_f32_e32 v94, v94
	v_exp_f32_e32 v95, v95
	v_add_f32_e32 v232, v232, v92
	v_add_f32_e32 v233, v233, v93
	s_nop 0
	v_add_f32_e32 v234, v234, v94
	v_add_f32_e32 v235, v235, v95
	v_cvt_pk_bf16_f32 v88, v88, v89
	v_cvt_pk_bf16_f32 v89, v90, v91
	v_cvt_pk_bf16_f32 v90, v92, v93
	v_cvt_pk_bf16_f32 v91, v94, v95
	s_nop 1
	s_waitcnt lgkmcnt(6)
	v_mfma_f32_32x32x16_bf16 v[0:15], v[88:91], v[180:183], v[0:15]
	s_waitcnt lgkmcnt(4)
	v_mfma_f32_32x32x16_bf16 v[16:31], v[88:91], v[184:187], v[16:31]
	s_waitcnt lgkmcnt(2)
	v_mfma_f32_32x32x16_bf16 v[32:47], v[88:91], v[188:191], v[32:47]
	s_waitcnt lgkmcnt(0)
	v_mfma_f32_32x32x16_bf16 v[48:63], v[88:91], v[192:195], v[48:63]
	s_cmp_eq_u32 s2, 0
	s_cbranch_scc0 .Lat2_skip_12
	s_add_i32 s6, s45, 2
	s_cmp_lt_u32 s6, s39
	s_cbranch_scc1 .Lat2_w3_13
	s_waitcnt vmcnt(0)
	s_branch .Lat2_wd_14

.Lat2_skip_12:
	s_mov_b32 s4, s59
	s_mov_b32 s59, s60
	s_mov_b32 s60, s61
	s_mov_b32 s61, s25
	s_mov_b32 s25, s4
	s_add_i32 s45, s45, 1
	s_mov_b32 s62, 0x41000000
	s_mov_b32 s47, 0
	s_branch .Lat2_main_2
.Lat2_band_3:
.Lat2_bandloop_4:
	s_sub_i32 s19, s45, s18
	v_add_u32_e32 v205, s59, v203
	ds_read_b128 v[116:119], v205 offset:0
	ds_read_b128 v[120:123], v205 offset:512
	ds_read_b128 v[124:127], v205 offset:2048
	ds_read_b128 v[128:131], v205 offset:2560
	ds_read_b128 v[132:135], v205 offset:4096
	ds_read_b128 v[136:139], v205 offset:4608
	ds_read_b128 v[140:143], v205 offset:6144
	ds_read_b128 v[144:147], v205 offset:6656
	s_add_i32 s6, s45, 2
	s_cmp_lt_u32 s6, s39
	s_cbranch_scc0 .Lat2_nodma_15
	s_add_i32 s4, s61, s16
	s_mov_b32 m0, s4
	s_lshl_b32 s5, s61, 1
	global_load_lds_dwordx4 v200, s[80:81]
	s_add_i32 s5, s5, s16
	s_add_i32 s5, s5, 0x8000
	s_mov_b32 m0, s5
	s_add_i32 s5, s5, 0x2000
	global_load_lds_dwordx4 v201, s[82:83]
	s_mov_b32 m0, s5
	s_nop 0
	global_load_lds_dwordx4 v202, s[82:83]
	s_add_u32 s80, s80, 0x10000
	s_addc_u32 s81, s81, 0
	s_add_u32 s82, s82, 0x10000
	s_addc_u32 s83, s83, 0
.Lat2_nodma_15:
	s_lshl_b32 s7, s59, 1
	v_add_u32_e32 v206, s7, v204
	s_waitcnt lgkmcnt(6)
	v_mfma_f32_32x32x16_bf16 v[64:79], v[116:119], v[148:151], v[100:115]
	v_mfma_f32_32x32x16_bf16 v[80:95], v[120:123], v[148:151], v[100:115]
	s_waitcnt lgkmcnt(4)
	v_mfma_f32_32x32x16_bf16 v[64:79], v[124:127], v[152:155], v[64:79]
	v_mfma_f32_32x32x16_bf16 v[80:95], v[128:131], v[152:155], v[80:95]
	s_waitcnt lgkmcnt(2)
	v_mfma_f32_32x32x16_bf16 v[64:79], v[132:135], v[156:159], v[64:79]
	v_mfma_f32_32x32x16_bf16 v[80:95], v[136:139], v[156:159], v[80:95]
	s_waitcnt lgkmcnt(0)
	v_mfma_f32_32x32x16_bf16 v[64:79], v[140:143], v[160:163], v[64:79]
	v_mfma_f32_32x32x16_bf16 v[80:95], v[144:147], v[160:163], v[80:95]
	ds_read_b64_tr_b16 v[164:165], v206 offset:0
	ds_read_b64_tr_b16 v[166:167], v206 offset:512
	ds_read_b64_tr_b16 v[168:169], v206 offset:4096
	ds_read_b64_tr_b16 v[170:171], v206 offset:4608
	ds_read_b64_tr_b16 v[172:173], v206 offset:8192
	ds_read_b64_tr_b16 v[174:175], v206 offset:8704
	ds_read_b64_tr_b16 v[176:177], v206 offset:12288
	ds_read_b64_tr_b16 v[178:179], v206 offset:12800
	ds_read_b64_tr_b16 v[180:181], v206 offset:1024
	ds_read_b64_tr_b16 v[182:183], v206 offset:1536
	ds_read_b64_tr_b16 v[184:185], v206 offset:5120
	ds_read_b64_tr_b16 v[186:187], v206 offset:5632
	ds_read_b64_tr_b16 v[188:189], v206 offset:9216
	ds_read_b64_tr_b16 v[190:191], v206 offset:9728
	ds_read_b64_tr_b16 v[192:193], v206 offset:13312
	ds_read_b64_tr_b16 v[194:195], v206 offset:13824
	s_lshl_b32 s7, s19, 6
	v_subrev_u32_e32 v226, s7, v218
	v_cmp_gt_i32_e64 s[0:1], 0, v226
	v_cmp_gt_i32_e64 s[14:15], 1, v226
	v_cmp_gt_i32_e64 vcc, 2, v226
	v_cndmask_b32_e64 v64, v64, v219, s[0:1]
	v_cmp_gt_i32_e64 s[0:1], 3, v226
	v_cndmask_b32_e64 v65, v65, v219, s[14:15]
	v_cmp_gt_i32_e64 s[14:15], 8, v226
	v_cndmask_b32_e64 v66, v66, v219, vcc
	v_cmp_gt_i32_e64 vcc, 9, v226
	v_cndmask_b32_e64 v67, v67, v219, s[0:1]
	v_cmp_gt_i32_e64 s[0:1], 10, v226
	v_cndmask_b32_e64 v68, v68, v219, s[14:15]
	v_cmp_gt_i32_e64 s[14:15], 11, v226
	v_cndmask_b32_e64 v69, v69, v219, vcc
	v_cmp_gt_i32_e64 vcc, 16, v226
	v_cndmask_b32_e64 v70, v70, v219, s[0:1]
	v_cmp_gt_i32_e64 s[0:1], 17, v226
	v_cndmask_b32_e64 v71, v71, v219, s[14:15]
	v_cmp_gt_i32_e64 s[14:15], 18, v226
	v_cndmask_b32_e64 v72, v72, v219, vcc
	v_cmp_gt_i32_e64 vcc, 19, v226
	v_cndmask_b32_e64 v73, v73, v219, s[0:1]
	v_cmp_gt_i32_e64 s[0:1], 24, v226
	v_cndmask_b32_e64 v74, v74, v219, s[14:15]
	v_cmp_gt_i32_e64 s[14:15], 25, v226
	v_cndmask_b32_e64 v75, v75, v219, vcc
	v_cmp_gt_i32_e64 vcc, 26, v226
	v_cndmask_b32_e64 v76, v76, v219, s[0:1]
	v_cmp_gt_i32_e64 s[0:1], 27, v226
	v_cndmask_b32_e64 v77, v77, v219, s[14:15]
	v_cmp_gt_i32_e64 s[14:15], 32, v226
	v_cndmask_b32_e64 v78, v78, v219, vcc
	v_cmp_gt_i32_e64 vcc, 33, v226
	v_cndmask_b32_e64 v79, v79, v219, s[0:1]
	v_cmp_gt_i32_e64 s[0:1], 34, v226
	v_cndmask_b32_e64 v80, v80, v219, s[14:15]
	v_cmp_gt_i32_e64 s[14:15], 35, v226
	v_cndmask_b32_e64 v81, v81, v219, vcc
	v_cmp_gt_i32_e64 vcc, 40, v226
	v_cndmask_b32_e64 v82, v82, v219, s[0:1]
	v_cmp_gt_i32_e64 s[0:1], 41, v226
	v_cndmask_b32_e64 v83, v83, v219, s[14:15]
	v_cmp_gt_i32_e64 s[14:15], 42, v226
	v_cndmask_b32_e64 v84, v84, v219, vcc
	v_cmp_gt_i32_e64 vcc, 43, v226
	v_cndmask_b32_e64 v85, v85, v219, s[0:1]
	v_cmp_gt_i32_e64 s[0:1], 48, v226
	v_cndmask_b32_e64 v86, v86, v219, s[14:15]
	v_cmp_gt_i32_e64 s[14:15], 49, v226
	v_cndmask_b32_e64 v87, v87, v219, vcc
	v_cmp_gt_i32_e64 vcc, 50, v226
	v_cndmask_b32_e64 v88, v88, v219, s[0:1]
	v_cmp_gt_i32_e64 s[0:1], 51, v226
	v_cndmask_b32_e64 v89, v89, v219, s[14:15]
	v_cmp_gt_i32_e64 s[14:15], 56, v226
	v_cndmask_b32_e64 v90, v90, v219, vcc
	v_cmp_gt_i32_e64 vcc, 57, v226
	v_cndmask_b32_e64 v91, v91, v219, s[0:1]
	v_cmp_gt_i32_e64 s[0:1], 58, v226
	v_cndmask_b32_e64 v92, v92, v219, s[14:15]
	v_cmp_gt_i32_e64 s[14:15], 59, v226
	v_cndmask_b32_e64 v93, v93, v219, vcc
	s_nop 0
	v_cndmask_b32_e64 v94, v94, v219, s[0:1]
	s_nop 0
	v_cndmask_b32_e64 v95, v95, v219, s[14:15]
	v_max3_f32 v215, v64, v65, v80
	v_max3_f32 v216, v66, v67, v81
	v_max3_f32 v215, v215, v82, v83
	v_max3_f32 v216, v216, v68, v69
	v_max3_f32 v215, v215, v70, v71
	v_max3_f32 v216, v216, v84, v85
	v_max3_f32 v215, v215, v86, v87
	v_max3_f32 v216, v216, v72, v73
	v_max3_f32 v215, v215, v74, v75
	v_max3_f32 v216, v216, v88, v89
	v_max3_f32 v215, v215, v90, v91
	v_max3_f32 v216, v216, v76, v77
	v_max3_f32 v215, v215, v78, v79
	v_max3_f32 v216, v216, v92, v93
	v_max3_f32 v215, v215, v94, v95
	v_max_f32_e32 v214, v215, v216
	v_mov_b32_e32 v215, v214
	s_nop 1
	v_permlane32_swap_b32_e32 v214, v215
	s_nop 0
	v_max_f32_e32 v214, v214, v215
	v_cmp_lt_f32_e32 vcc, s62, v214
	s_cmp_lg_u64 vcc, 0
	s_cbranch_scc1 .Lat2_resc_16

.Lat2_skip_21:
	s_mov_b32 s4, s59
	s_mov_b32 s59, s60
	s_mov_b32 s60, s61
	s_mov_b32 s61, s25
	s_mov_b32 s25, s4
	s_add_i32 s45, s45, 1
	s_mov_b32 s62, 0x41000000
	s_mov_b32 s47, 0
	s_cmp_lt_u32 s45, s39
	s_cbranch_scc1 .Lat2_bandloop_4
	v_add_f32_e32 v232, v232, v233
	v_add_f32_e32 v234, v234, v235
	v_add_f32_e32 v216, v232, v234
	v_mov_b32_e32 v215, v216
	s_nop 1
	v_permlane32_swap_b32_e32 v216, v215
	s_nop 0
	v_add_f32_e32 v216, v216, v215
	v_rcp_f32_e32 v217, v216
	s_nop 0
	ds_write_b32 v220, v217
	s_waitcnt lgkmcnt(0)
	ds_read_b128 v[116:119], v221 offset:0
	ds_read_b128 v[120:123], v221 offset:32
	ds_read_b128 v[124:127], v221 offset:64
	ds_read_b128 v[128:131], v221 offset:96
	v_add_u32_e32 v229, 0x8000, v224
	s_waitcnt lgkmcnt(0)
	v_mul_f32_e32 v0, v0, v116
	v_mul_f32_e32 v1, v1, v117
	v_cvt_pk_bf16_f32 v0, v0, v1
	ds_write_b16 v222, v0 offset:0
	ds_write_b16_d16_hi v222, v0 offset:64
	v_mul_f32_e32 v2, v2, v118
	v_mul_f32_e32 v3, v3, v119
	v_cvt_pk_bf16_f32 v2, v2, v3
	ds_write_b16 v222, v2 offset:128
	ds_write_b16_d16_hi v222, v2 offset:192
	v_mul_f32_e32 v4, v4, v120
	v_mul_f32_e32 v5, v5, v121
	v_cvt_pk_bf16_f32 v4, v4, v5
	ds_write_b16 v222, v4 offset:512
	ds_write_b16_d16_hi v222, v4 offset:576
	v_mul_f32_e32 v6, v6, v122
	v_mul_f32_e32 v7, v7, v123
	v_cvt_pk_bf16_f32 v6, v6, v7
	ds_write_b16 v222, v6 offset:640
	ds_write_b16_d16_hi v222, v6 offset:704
	v_mul_f32_e32 v8, v8, v124
	v_mul_f32_e32 v9, v9, v125
	v_cvt_pk_bf16_f32 v8, v8, v9
	ds_write_b16 v222, v8 offset:1024
	ds_write_b16_d16_hi v222, v8 offset:1088
	v_mul_f32_e32 v10, v10, v126
	v_mul_f32_e32 v11, v11, v127
	v_cvt_pk_bf16_f32 v10, v10, v11
	ds_write_b16 v222, v10 offset:1152
	ds_write_b16_d16_hi v222, v10 offset:1216
	v_mul_f32_e32 v12, v12, v128
	v_mul_f32_e32 v13, v13, v129
	v_cvt_pk_bf16_f32 v12, v12, v13
	ds_write_b16 v222, v12 offset:1536
	ds_write_b16_d16_hi v222, v12 offset:1600
	v_mul_f32_e32 v14, v14, v130
	v_mul_f32_e32 v15, v15, v131
	v_cvt_pk_bf16_f32 v14, v14, v15
	ds_write_b16 v222, v14 offset:1664
	ds_write_b16_d16_hi v222, v14 offset:1728
	s_waitcnt lgkmcnt(0)
	ds_read_b128 v[132:135], v223
	ds_read_b128 v[136:139], v223 offset:1024
	s_waitcnt lgkmcnt(1)
	global_store_dwordx4 v224, v[132:135], s[78:79] offset:0
	s_waitcnt lgkmcnt(0)
	global_store_dwordx4 v229, v[136:139], s[78:79] offset:0
	v_mul_f32_e32 v16, v16, v116
	v_mul_f32_e32 v17, v17, v117
	v_cvt_pk_bf16_f32 v16, v16, v17
	ds_write_b16 v222, v16 offset:0
	ds_write_b16_d16_hi v222, v16 offset:64
	v_mul_f32_e32 v18, v18, v118
	v_mul_f32_e32 v19, v19, v119
	v_cvt_pk_bf16_f32 v18, v18, v19
	ds_write_b16 v222, v18 offset:128
	ds_write_b16_d16_hi v222, v18 offset:192
	v_mul_f32_e32 v20, v20, v120
	v_mul_f32_e32 v21, v21, v121
	v_cvt_pk_bf16_f32 v20, v20, v21
	ds_write_b16 v222, v20 offset:512
	ds_write_b16_d16_hi v222, v20 offset:576
	v_mul_f32_e32 v22, v22, v122
	v_mul_f32_e32 v23, v23, v123
	v_cvt_pk_bf16_f32 v22, v22, v23
	ds_write_b16 v222, v22 offset:640
	ds_write_b16_d16_hi v222, v22 offset:704
	v_mul_f32_e32 v24, v24, v124
	v_mul_f32_e32 v25, v25, v125
	v_cvt_pk_bf16_f32 v24, v24, v25
	ds_write_b16 v222, v24 offset:1024
	ds_write_b16_d16_hi v222, v24 offset:1088
	v_mul_f32_e32 v26, v26, v126
	v_mul_f32_e32 v27, v27, v127
	v_cvt_pk_bf16_f32 v26, v26, v27
	ds_write_b16 v222, v26 offset:1152
	ds_write_b16_d16_hi v222, v26 offset:1216
	v_mul_f32_e32 v28, v28, v128
	v_mul_f32_e32 v29, v29, v129
	v_cvt_pk_bf16_f32 v28, v28, v29
	ds_write_b16 v222, v28 offset:1536
	ds_write_b16_d16_hi v222, v28 offset:1600
	v_mul_f32_e32 v30, v30, v130
	v_mul_f32_e32 v31, v31, v131
	v_cvt_pk_bf16_f32 v30, v30, v31
	ds_write_b16 v222, v30 offset:1664
	ds_write_b16_d16_hi v222, v30 offset:1728
	s_waitcnt lgkmcnt(0)
	ds_read_b128 v[132:135], v223
	ds_read_b128 v[136:139], v223 offset:1024
	s_waitcnt lgkmcnt(1)
	global_store_dwordx4 v224, v[132:135], s[78:79] offset:64
	s_waitcnt lgkmcnt(0)
	global_store_dwordx4 v229, v[136:139], s[78:79] offset:64
	v_mul_f32_e32 v32, v32, v116
	v_mul_f32_e32 v33, v33, v117
	v_cvt_pk_bf16_f32 v32, v32, v33
	ds_write_b16 v222, v32 offset:0
	ds_write_b16_d16_hi v222, v32 offset:64
	v_mul_f32_e32 v34, v34, v118
	v_mul_f32_e32 v35, v35, v119
	v_cvt_pk_bf16_f32 v34, v34, v35
	ds_write_b16 v222, v34 offset:128
	ds_write_b16_d16_hi v222, v34 offset:192
	v_mul_f32_e32 v36, v36, v120
	v_mul_f32_e32 v37, v37, v121
	v_cvt_pk_bf16_f32 v36, v36, v37
	ds_write_b16 v222, v36 offset:512
	ds_write_b16_d16_hi v222, v36 offset:576
	v_mul_f32_e32 v38, v38, v122
	v_mul_f32_e32 v39, v39, v123
	v_cvt_pk_bf16_f32 v38, v38, v39
	ds_write_b16 v222, v38 offset:640
	ds_write_b16_d16_hi v222, v38 offset:704
	v_mul_f32_e32 v40, v40, v124
	v_mul_f32_e32 v41, v41, v125
	v_cvt_pk_bf16_f32 v40, v40, v41
	ds_write_b16 v222, v40 offset:1024
	ds_write_b16_d16_hi v222, v40 offset:1088
	v_mul_f32_e32 v42, v42, v126
	v_mul_f32_e32 v43, v43, v127
	v_cvt_pk_bf16_f32 v42, v42, v43
	ds_write_b16 v222, v42 offset:1152
	ds_write_b16_d16_hi v222, v42 offset:1216
	v_mul_f32_e32 v44, v44, v128
	v_mul_f32_e32 v45, v45, v129
	v_cvt_pk_bf16_f32 v44, v44, v45
	ds_write_b16 v222, v44 offset:1536
	ds_write_b16_d16_hi v222, v44 offset:1600
	v_mul_f32_e32 v46, v46, v130
	v_mul_f32_e32 v47, v47, v131
	v_cvt_pk_bf16_f32 v46, v46, v47
	ds_write_b16 v222, v46 offset:1664
	ds_write_b16_d16_hi v222, v46 offset:1728
	s_waitcnt lgkmcnt(0)
	ds_read_b128 v[132:135], v223
	ds_read_b128 v[136:139], v223 offset:1024
	s_waitcnt lgkmcnt(1)
	global_store_dwordx4 v224, v[132:135], s[78:79] offset:128
	s_waitcnt lgkmcnt(0)
	global_store_dwordx4 v229, v[136:139], s[78:79] offset:128
	v_mul_f32_e32 v48, v48, v116
	v_mul_f32_e32 v49, v49, v117
	v_cvt_pk_bf16_f32 v48, v48, v49
	ds_write_b16 v222, v48 offset:0
	ds_write_b16_d16_hi v222, v48 offset:64
	v_mul_f32_e32 v50, v50, v118
	v_mul_f32_e32 v51, v51, v119
	v_cvt_pk_bf16_f32 v50, v50, v51
	ds_write_b16 v222, v50 offset:128
	ds_write_b16_d16_hi v222, v50 offset:192
	v_mul_f32_e32 v52, v52, v120
	v_mul_f32_e32 v53, v53, v121
	v_cvt_pk_bf16_f32 v52, v52, v53
	ds_write_b16 v222, v52 offset:512
	ds_write_b16_d16_hi v222, v52 offset:576
	v_mul_f32_e32 v54, v54, v122
	v_mul_f32_e32 v55, v55, v123
	v_cvt_pk_bf16_f32 v54, v54, v55
	ds_write_b16 v222, v54 offset:640
	ds_write_b16_d16_hi v222, v54 offset:704
	v_mul_f32_e32 v56, v56, v124
	v_mul_f32_e32 v57, v57, v125
	v_cvt_pk_bf16_f32 v56, v56, v57
	ds_write_b16 v222, v56 offset:1024
	ds_write_b16_d16_hi v222, v56 offset:1088
	v_mul_f32_e32 v58, v58, v126
	v_mul_f32_e32 v59, v59, v127
	v_cvt_pk_bf16_f32 v58, v58, v59
	ds_write_b16 v222, v58 offset:1152
	ds_write_b16_d16_hi v222, v58 offset:1216
	v_mul_f32_e32 v60, v60, v128
	v_mul_f32_e32 v61, v61, v129
	v_cvt_pk_bf16_f32 v60, v60, v61
	ds_write_b16 v222, v60 offset:1536
	ds_write_b16_d16_hi v222, v60 offset:1600
	v_mul_f32_e32 v62, v62, v130
	v_mul_f32_e32 v63, v63, v131
	v_cvt_pk_bf16_f32 v62, v62, v63
	ds_write_b16 v222, v62 offset:1664
	ds_write_b16_d16_hi v222, v62 offset:1728
	s_waitcnt lgkmcnt(0)
	ds_read_b128 v[132:135], v223
	ds_read_b128 v[136:139], v223 offset:1024
	s_waitcnt lgkmcnt(1)
	global_store_dwordx4 v224, v[132:135], s[78:79] offset:192
	s_waitcnt lgkmcnt(0)
	global_store_dwordx4 v229, v[136:139], s[78:79] offset:192
	s_add_i32 s26, s26, 1
	s_cmp_lt_u32 s26, 4
	s_cbranch_scc1 .Lat2_unit_1
	s_branch .Lat2_done_5
.Lat2_resc_7:
	v_max_f32_e32 v212, s47, v214
	v_add_f32_e32 v210, v210, v212
	v_exp_f32_e64 v217, -v212
	v_sub_f32_e32 v64, v64, v212
	v_sub_f32_e32 v65, v65, v212
	v_sub_f32_e32 v66, v66, v212
	v_sub_f32_e32 v67, v67, v212
	v_sub_f32_e32 v68, v68, v212
	v_sub_f32_e32 v69, v69, v212
	v_sub_f32_e32 v70, v70, v212
	v_sub_f32_e32 v71, v71, v212
	v_sub_f32_e32 v72, v72, v212
	v_sub_f32_e32 v73, v73, v212
	v_sub_f32_e32 v74, v74, v212
	v_sub_f32_e32 v75, v75, v212
	v_sub_f32_e32 v76, v76, v212
	v_sub_f32_e32 v77, v77, v212
	v_sub_f32_e32 v78, v78, v212
	v_sub_f32_e32 v79, v79, v212
	v_sub_f32_e32 v80, v80, v212
	v_sub_f32_e32 v81, v81, v212
	v_sub_f32_e32 v82, v82, v212
	v_sub_f32_e32 v83, v83, v212
	v_sub_f32_e32 v84, v84, v212
	v_sub_f32_e32 v85, v85, v212
	v_sub_f32_e32 v86, v86, v212
	v_sub_f32_e32 v87, v87, v212
	v_sub_f32_e32 v88, v88, v212
	v_sub_f32_e32 v89, v89, v212
	v_sub_f32_e32 v90, v90, v212
	v_sub_f32_e32 v91, v91, v212
	v_sub_f32_e32 v92, v92, v212
	v_sub_f32_e32 v93, v93, v212
	v_sub_f32_e32 v94, v94, v212
	v_sub_f32_e32 v95, v95, v212
	v_sub_f32_e32 v100, 0, v210
	v_sub_f32_e32 v101, 0, v210
	v_sub_f32_e32 v102, 0, v210
	v_sub_f32_e32 v103, 0, v210
	v_sub_f32_e32 v104, 0, v210
	v_sub_f32_e32 v105, 0, v210
	v_sub_f32_e32 v106, 0, v210
	v_sub_f32_e32 v107, 0, v210
	v_sub_f32_e32 v108, 0, v210
	v_sub_f32_e32 v109, 0, v210
	v_sub_f32_e32 v110, 0, v210
	v_sub_f32_e32 v111, 0, v210
	v_sub_f32_e32 v112, 0, v210
	v_sub_f32_e32 v113, 0, v210
	v_sub_f32_e32 v114, 0, v210
	v_sub_f32_e32 v115, 0, v210
	v_mul_f32_e32 v232, v232, v217
	v_mul_f32_e32 v233, v233, v217
	v_mul_f32_e32 v234, v234, v217
	v_mul_f32_e32 v235, v235, v217
	s_waitcnt lgkmcnt(0)
	ds_write_b32 v220, v217
	s_waitcnt lgkmcnt(0)
	ds_read_b128 v[116:119], v221 offset:0
	ds_read_b128 v[120:123], v221 offset:32
	ds_read_b128 v[124:127], v221 offset:64
	ds_read_b128 v[128:131], v221 offset:96
	s_waitcnt lgkmcnt(0)
	v_mul_f32_e32 v0, v0, v116
	v_mul_f32_e32 v1, v1, v117
	v_mul_f32_e32 v2, v2, v118
	v_mul_f32_e32 v3, v3, v119
	v_mul_f32_e32 v4, v4, v120
	v_mul_f32_e32 v5, v5, v121
	v_mul_f32_e32 v6, v6, v122
	v_mul_f32_e32 v7, v7, v123
	v_mul_f32_e32 v8, v8, v124
	v_mul_f32_e32 v9, v9, v125
	v_mul_f32_e32 v10, v10, v126
	v_mul_f32_e32 v11, v11, v127
	v_mul_f32_e32 v12, v12, v128
	v_mul_f32_e32 v13, v13, v129
	v_mul_f32_e32 v14, v14, v130
	v_mul_f32_e32 v15, v15, v131
	v_mul_f32_e32 v16, v16, v116
	v_mul_f32_e32 v17, v17, v117
	v_mul_f32_e32 v18, v18, v118
	v_mul_f32_e32 v19, v19, v119
	v_mul_f32_e32 v20, v20, v120
	v_mul_f32_e32 v21, v21, v121
	v_mul_f32_e32 v22, v22, v122
	v_mul_f32_e32 v23, v23, v123
	v_mul_f32_e32 v24, v24, v124
	v_mul_f32_e32 v25, v25, v125
	v_mul_f32_e32 v26, v26, v126
	v_mul_f32_e32 v27, v27, v127
	v_mul_f32_e32 v28, v28, v128
	v_mul_f32_e32 v29, v29, v129
	v_mul_f32_e32 v30, v30, v130
	v_mul_f32_e32 v31, v31, v131
	v_mul_f32_e32 v32, v32, v116
	v_mul_f32_e32 v33, v33, v117
	v_mul_f32_e32 v34, v34, v118
	v_mul_f32_e32 v35, v35, v119
	v_mul_f32_e32 v36, v36, v120
	v_mul_f32_e32 v37, v37, v121
	v_mul_f32_e32 v38, v38, v122
	v_mul_f32_e32 v39, v39, v123
	v_mul_f32_e32 v40, v40, v124
	v_mul_f32_e32 v41, v41, v125
	v_mul_f32_e32 v42, v42, v126
	v_mul_f32_e32 v43, v43, v127
	v_mul_f32_e32 v44, v44, v128
	v_mul_f32_e32 v45, v45, v129
	v_mul_f32_e32 v46, v46, v130
	v_mul_f32_e32 v47, v47, v131
	v_mul_f32_e32 v48, v48, v116
	v_mul_f32_e32 v49, v49, v117
	v_mul_f32_e32 v50, v50, v118
	v_mul_f32_e32 v51, v51, v119
	v_mul_f32_e32 v52, v52, v120
	v_mul_f32_e32 v53, v53, v121
	v_mul_f32_e32 v54, v54, v122
	v_mul_f32_e32 v55, v55, v123
	v_mul_f32_e32 v56, v56, v124
	v_mul_f32_e32 v57, v57, v125
	v_mul_f32_e32 v58, v58, v126
	v_mul_f32_e32 v59, v59, v127
	v_mul_f32_e32 v60, v60, v128
	v_mul_f32_e32 v61, v61, v129
	v_mul_f32_e32 v62, v62, v130
	v_mul_f32_e32 v63, v63, v131
	s_branch .Lat2_back_8
